# prologue x->bf16+sumsq loop: the row's 8 loads issued together with counted waits
# speedup vs baseline: 1.0277x; 1.0020x over previous
.LBB0_9:
	s_waitcnt lgkmcnt(0)
	global_load_dwordx4 v[18:21], v[6:7], off offset:-4096
	global_load_dwordx4 v[22:25], v[6:7], off offset:-3072
	global_load_dwordx4 v[26:29], v[6:7], off offset:-2048
	global_load_dwordx4 v[30:33], v[6:7], off offset:-1024
	global_load_dwordx4 v[34:37], v[6:7], off
	global_load_dwordx4 v[38:41], v[6:7], off offset:1024
	global_load_dwordx4 v[42:45], v[6:7], off offset:2048
	global_load_dwordx4 v[46:49], v[6:7], off offset:3072
	s_waitcnt vmcnt(7)
	v_cvt_pk_bf16_f32 v50, v18, v19
	v_cvt_pk_bf16_f32 v51, v20, v21
	global_store_dwordx2 v[8:9], v[50:51], off offset:-2048
	v_mul_f32_e32 v19, v19, v19
	v_mul_f32_e32 v21, v21, v21
	v_fmac_f32_e32 v19, v18, v18
	v_fmac_f32_e32 v21, v20, v20
	v_add_f32_e32 v18, v19, v21
	s_waitcnt vmcnt(7)
	v_cvt_pk_bf16_f32 v52, v22, v23
	v_cvt_pk_bf16_f32 v53, v24, v25
	global_store_dwordx2 v[8:9], v[52:53], off offset:-1536
	v_mul_f32_e32 v19, v23, v23
	v_mul_f32_e32 v20, v25, v25
	v_fmac_f32_e32 v19, v22, v22
	v_fmac_f32_e32 v20, v24, v24
	v_add_f32_e32 v19, v19, v20
	v_add_f32_e32 v18, v18, v19
	s_waitcnt vmcnt(7)
	v_cvt_pk_bf16_f32 v50, v26, v27
	v_cvt_pk_bf16_f32 v51, v28, v29
	global_store_dwordx2 v[8:9], v[50:51], off offset:-1024
	v_mul_f32_e32 v19, v27, v27
	v_mul_f32_e32 v20, v29, v29
	v_fmac_f32_e32 v19, v26, v26
	v_fmac_f32_e32 v20, v28, v28
	v_add_f32_e32 v19, v19, v20
	v_add_f32_e32 v18, v18, v19
	s_waitcnt vmcnt(7)
	v_cvt_pk_bf16_f32 v52, v30, v31
	v_cvt_pk_bf16_f32 v53, v32, v33
	global_store_dwordx2 v[8:9], v[52:53], off offset:-512
	v_mul_f32_e32 v19, v31, v31
	v_mul_f32_e32 v20, v33, v33
	v_fmac_f32_e32 v19, v30, v30
	v_fmac_f32_e32 v20, v32, v32
	v_add_f32_e32 v19, v19, v20
	v_add_f32_e32 v18, v18, v19
	s_waitcnt vmcnt(7)
	v_cvt_pk_bf16_f32 v50, v34, v35
	v_cvt_pk_bf16_f32 v51, v36, v37
	global_store_dwordx2 v[8:9], v[50:51], off
	v_mul_f32_e32 v19, v35, v35
	v_mul_f32_e32 v20, v37, v37
	v_fmac_f32_e32 v19, v34, v34
	v_fmac_f32_e32 v20, v36, v36
	v_add_f32_e32 v19, v19, v20
	v_add_f32_e32 v18, v18, v19
	s_waitcnt vmcnt(7)
	v_cvt_pk_bf16_f32 v52, v38, v39
	v_cvt_pk_bf16_f32 v53, v40, v41
	global_store_dwordx2 v[8:9], v[52:53], off offset:512
	v_mul_f32_e32 v19, v39, v39
	v_mul_f32_e32 v20, v41, v41
	v_fmac_f32_e32 v19, v38, v38
	v_fmac_f32_e32 v20, v40, v40
	v_add_f32_e32 v19, v19, v20
	v_add_f32_e32 v18, v18, v19
	s_waitcnt vmcnt(7)
	v_cvt_pk_bf16_f32 v50, v42, v43
	v_cvt_pk_bf16_f32 v51, v44, v45
	global_store_dwordx2 v[8:9], v[50:51], off offset:1024
	v_mul_f32_e32 v19, v43, v43
	v_mul_f32_e32 v20, v45, v45
	v_fmac_f32_e32 v19, v42, v42
	v_fmac_f32_e32 v20, v44, v44
	v_add_f32_e32 v19, v19, v20
	v_add_f32_e32 v18, v18, v19
	s_waitcnt vmcnt(7)
	v_cvt_pk_bf16_f32 v52, v46, v47
	v_cvt_pk_bf16_f32 v53, v48, v49
	global_store_dwordx2 v[8:9], v[52:53], off offset:1536
	v_mul_f32_e32 v19, v47, v47
	v_mul_f32_e32 v20, v49, v49
	v_fmac_f32_e32 v19, v46, v46
	v_fmac_f32_e32 v20, v48, v48
	v_add_f32_e32 v19, v19, v20
	v_add_f32_e32 v18, v18, v19
	ds_bpermute_b32 v19, v12, v18
	s_waitcnt lgkmcnt(0)
	v_add_f32_e32 v18, v18, v19
	ds_bpermute_b32 v19, v13, v18
	s_waitcnt lgkmcnt(0)
	v_add_f32_e32 v18, v18, v19
	ds_bpermute_b32 v19, v14, v18
	s_waitcnt lgkmcnt(0)
	v_add_f32_e32 v18, v18, v19
	ds_bpermute_b32 v19, v15, v18
	s_waitcnt lgkmcnt(0)
	v_add_f32_e32 v18, v18, v19
	ds_bpermute_b32 v19, v16, v18
	s_waitcnt lgkmcnt(0)
	v_add_f32_e32 v18, v18, v19
	ds_bpermute_b32 v19, v17, v18
	s_and_saveexec_b64 s[6:7], vcc
	s_cbranch_execz .LBB0_8
	s_waitcnt lgkmcnt(0)
	v_add_f32_e32 v18, v18, v19
	global_store_dword v[4:5], v18, off
	s_branch .LBB0_8
